# one static s_setprio 1 for waves 4-7 during the attention/LRU phase (reset at the phase end)
# speedup vs baseline: 1.0075x; 1.0050x over previous
.LBB0_194:
	v_readfirstlane_b32 s100, v160
	s_nop 3
	s_lshr_b32 s100, s100, 6
	s_cmp_ge_u32 s100, 4
	s_cbranch_scc0 .Lprio_skip_L0
	s_setprio 1

.LBB0_314:
	s_setprio 0
	s_cmp_lt_i32 s92, 4
	s_cselect_b64 s[0:1], -1, 0
	s_cmp_gt_i32 s93, 3
	s_cselect_b64 s[4:5], -1, 0
	s_and_b64 s[0:1], s[0:1], s[4:5]
	s_andn2_b64 vcc, exec, s[0:1]
	s_cbranch_vccnz .LBB0_385
	s_load_dword s0, s[96:97], 0xd0
	s_add_u32 s6, s96, 0xd0
	s_addc_u32 s7, s97, 0
	s_cmpk_gt_i32 s2, 0x3ff
	v_readfirstlane_b32 s1, v160
	s_cbranch_scc1 .LBB0_335
	s_ashr_i32 s3, s2, 31
	s_lshr_b32 s4, s3, 29
	s_add_i32 s10, s2, s4
	s_and_b32 s4, s10, -8
	s_sub_i32 s9, s2, s4
	s_cmp_gt_i32 s9, -1
	s_cbranch_scc0 .LBB0_318
	s_lshl_b32 s8, s9, 7
	s_ashr_i32 s4, s10, 3
	s_cbranch_execz .LBB0_319
	s_branch .LBB0_320

.LBB0_1380:
	s_setprio 0
	s_cmp_lt_i32 s92, 17
	s_cselect_b64 s[0:1], -1, 0
	s_cmp_gt_i32 s93, 16
	s_cselect_b64 s[4:5], -1, 0
	s_and_b64 s[0:1], s[0:1], s[4:5]
	s_andn2_b64 vcc, exec, s[0:1]
	s_cbranch_vccnz .LBB0_1451
	s_load_dword s0, s[96:97], 0xd0
	s_add_u32 s6, s96, 0xd0
	s_addc_u32 s7, s97, 0
	s_cmpk_gt_i32 s2, 0x3ff
	v_readfirstlane_b32 s1, v160
	s_cbranch_scc1 .LBB0_1401
	s_ashr_i32 s3, s2, 31
	s_lshr_b32 s4, s3, 29
	s_add_i32 s10, s2, s4
	s_and_b32 s4, s10, -8
	s_sub_i32 s9, s2, s4
	s_cmp_gt_i32 s9, -1
	s_cbranch_scc0 .LBB0_1384
	s_lshl_b32 s8, s9, 7
	s_ashr_i32 s4, s10, 3
	s_cbranch_execz .LBB0_1385
	s_branch .LBB0_1386
